# out-projection GEMM k-loop software-pipelined like the other GEMMs (token operand re-based at the source-buffer switch after 8 k-steps), first MFMA per accumulator with C=0
# speedup vs baseline: 1.0015x; 1.0015x over previous
.LBB0_2000:
	s_cmp_lt_i32 s30, 0
	s_cbranch_scc1 .LBB0_1993
	s_mul_i32 s41, s30, 0xc0000
	s_mul_hi_u32 s40, s30, 0xc0000
	s_add_u32 s34, s14, s41
	v_mov_b32_e32 v0, v184
	s_addc_u32 s35, s15, s40
	s_ashr_i32 s11, s10, 31
	s_lshl_b64 s[2:3], s[10:11], 18
	v_ashrrev_i32_e32 v1, 6, v0
	v_bfe_u32 v2, v0, 3, 3
	v_readfirstlane_b32 s42, v1
	s_add_u32 s36, s16, s2
	v_bitop3_b32 v4, v2, v0, 7 bitop3:0x78
	v_lshl_or_b32 v139, s42, 5, v2
	s_addc_u32 s37, s17, s3
	v_lshlrev_b32_e32 v138, 4, v4
	s_lshl_b32 s13, s42, 2
	v_mul_lo_u32 v4, v139, s24
	s_lshl_b32 s8, s42, 12
	s_lshl_b64 s[38:39], s[10:11], 19
	s_waitcnt lgkmcnt(0)
	s_barrier
	v_or_b32_e32 v4, v4, v138
	s_mov_b32 m0, s8
	s_or_b32 s11, s13, 1
	global_load_lds_dwordx4 v4, s[34:35]
	v_lshl_or_b32 v4, v139, 10, v138
	s_add_i32 m0, s8, 0x8000
	v_lshl_or_b32 v140, s11, 3, v2
	global_load_lds_dwordx4 v4, s[36:37]
	v_mul_lo_u32 v4, v140, s24
	s_lshl_b32 s11, s11, 10
	v_or_b32_e32 v4, v4, v138
	s_mov_b32 m0, s11
	s_or_b32 s12, s13, 2
	global_load_lds_dwordx4 v4, s[34:35]
	v_lshl_or_b32 v4, v140, 10, v138
	s_add_i32 m0, s11, 0x8000
	v_lshl_or_b32 v144, s12, 3, v2
	global_load_lds_dwordx4 v4, s[36:37]
	v_mul_lo_u32 v4, v144, s24
	s_lshl_b32 s12, s12, 10
	v_or_b32_e32 v4, v4, v138
	s_mov_b32 m0, s12
	s_or_b32 s13, s13, 3
	global_load_lds_dwordx4 v4, s[34:35]
	v_lshl_or_b32 v4, v144, 10, v138
	s_add_i32 m0, s12, 0x8000
	v_lshl_or_b32 v145, s13, 3, v2
	global_load_lds_dwordx4 v4, s[36:37]
	v_mul_lo_u32 v4, v145, s24
	s_lshl_b32 s13, s13, 10
	v_or_b32_e32 v4, v4, v138
	s_mov_b32 m0, s13
	v_and_b32_e32 v3, 7, v0
	global_load_lds_dwordx4 v4, s[34:35]
	v_lshl_or_b32 v4, v145, 10, v138
	s_add_i32 m0, s13, 0x8000
	s_add_u32 s31, s18, s38
	global_load_lds_dwordx4 v4, s[36:37]
	v_bfe_u32 v4, v0, 4, 2
	v_bitop3_b32 v5, v4, v0, 7 bitop3:0x78
	v_lshlrev_b32_e32 v146, 4, v5
	v_lshlrev_b32_e32 v5, 7, v0
	v_and_b32_e32 v5, 0x780, v5
	v_lshlrev_b32_e32 v0, 6, v0
	s_addc_u32 s34, s19, s39
	v_and_or_b32 v141, v0, s26, v5
	v_bitop3_b32 v0, v4, v3, 4 bitop3:0x36
	s_mul_i32 s35, s42, 0x18000
	s_add_u32 s36, s20, s41
	v_lshlrev_b32_e32 v142, 4, v0
	v_mul_u32_u24_e32 v0, 0xc00, v2
	s_addc_u32 s37, s21, s40
	s_add_i32 s38, s35, 0xc000
	v_or3_b32 v132, v0, s35, v138
	v_mov_b32_e32 v0, s38
	v_lshl_add_u64 v[128:129], s[36:37], 0, v[132:133]
	v_add_u32_e32 v132, 0x6000, v132
	v_mad_u32_u24 v0, v2, s24, v0
	s_add_i32 s35, s35, 0x12000
	s_waitcnt vmcnt(0)
	v_lshl_add_u64 v[130:131], s[36:37], 0, v[132:133]
	v_or_b32_e32 v132, v0, v138
	v_mov_b32_e32 v0, s35
	s_waitcnt lgkmcnt(0)
	s_barrier
	v_mad_u32_u24 v0, v2, s24, v0
	v_lshlrev_b32_e32 v1, 13, v1
	v_lshl_add_u64 v[134:135], s[36:37], 0, v[132:133]
	v_or_b32_e32 v132, v0, v138
	s_add_u32 s35, s22, s2
	v_and_or_b32 v143, v1, s25, v5
	v_lshl_add_u64 v[136:137], s[36:37], 0, v[132:133]
	s_addc_u32 s36, s23, s3
	s_mov_b32 s37, 0
	s_mov_b64 s[2:3], 0
	s_mov_b32 s38, 0
.LBB0_2002:
	s_waitcnt lgkmcnt(0)
	s_mov_b32 s99, 0x10000
	s_mov_b32 s100, 0x80
	s_mov_b32 s101, 0
	s_mov_b32 s42, s35
	s_mov_b32 s43, s36
	v_mov_b32_e32 v243, 0
	v_lshl_or_b32 v242, v139, 10, v138
	v_lshl_add_u64 v[234:235], s[42:43], 0, v[242:243]
	v_lshl_or_b32 v242, v140, 10, v138
	v_lshl_add_u64 v[236:237], s[42:43], 0, v[242:243]
	v_lshl_or_b32 v242, v144, 10, v138
	v_lshl_add_u64 v[238:239], s[42:43], 0, v[242:243]
	v_lshl_or_b32 v242, v145, 10, v138
	v_lshl_add_u64 v[240:241], s[42:43], 0, v[242:243]
	s_add_i32 m0, s8, 0x10000
	s_nop 0
	global_load_lds_dwordx4 v[128:129], off
	v_lshl_add_u64 v[128:129], v[128:129], 0, s[100:101]
	s_add_i32 m0, s8, 0x18000
	s_nop 0
	global_load_lds_dwordx4 v[234:235], off
	v_lshl_add_u64 v[234:235], v[234:235], 0, s[100:101]
	s_add_i32 m0, s11, 0x10000
	s_nop 0
	global_load_lds_dwordx4 v[130:131], off
	v_lshl_add_u64 v[130:131], v[130:131], 0, s[100:101]
	s_add_i32 m0, s11, 0x18000
	s_nop 0
	global_load_lds_dwordx4 v[236:237], off
	v_lshl_add_u64 v[236:237], v[236:237], 0, s[100:101]
	s_add_i32 m0, s12, 0x10000
	s_nop 0
	global_load_lds_dwordx4 v[134:135], off
	v_lshl_add_u64 v[134:135], v[134:135], 0, s[100:101]
	s_add_i32 m0, s12, 0x18000
	s_nop 0
	global_load_lds_dwordx4 v[238:239], off
	v_lshl_add_u64 v[238:239], v[238:239], 0, s[100:101]
	s_add_i32 m0, s13, 0x10000
	s_nop 0
	global_load_lds_dwordx4 v[136:137], off
	v_lshl_add_u64 v[136:137], v[136:137], 0, s[100:101]
	s_add_i32 m0, s13, 0x18000
	s_nop 0
	global_load_lds_dwordx4 v[240:241], off
	v_lshl_add_u64 v[240:241], v[240:241], 0, s[100:101]
	v_add_u32_e32 v160, v146, v143
	v_add_u32_e32 v132, v146, v141
	ds_read_b128 v[148:151], v160 offset:32768
	ds_read_b128 v[152:155], v160 offset:34816
	ds_read_b128 v[156:159], v160 offset:36864
	ds_read_b128 v[160:163], v160 offset:38912
	ds_read_b128 v[164:167], v132 offset:0
	ds_read_b128 v[168:171], v132 offset:2048
	ds_read_b128 v[172:175], v132 offset:4096
	ds_read_b128 v[176:179], v132 offset:6144
	ds_read_b128 v[180:183], v132 offset:8192
	ds_read_b128 v[186:189], v132 offset:10240
	ds_read_b128 v[190:193], v132 offset:12288
	ds_read_b128 v[194:197], v132 offset:14336
	s_waitcnt lgkmcnt(4)
	v_mfma_f32_16x16x32_bf16 v[124:127], v[164:167], v[148:151], 0
	v_mfma_f32_16x16x32_bf16 v[120:123], v[164:167], v[152:155], 0
	v_mfma_f32_16x16x32_bf16 v[116:119], v[164:167], v[156:159], 0
	v_mfma_f32_16x16x32_bf16 v[112:115], v[164:167], v[160:163], 0
	v_mfma_f32_16x16x32_bf16 v[108:111], v[168:171], v[148:151], 0
	v_mfma_f32_16x16x32_bf16 v[104:107], v[168:171], v[152:155], 0
	v_mfma_f32_16x16x32_bf16 v[100:103], v[168:171], v[156:159], 0
	v_mfma_f32_16x16x32_bf16 v[96:99], v[168:171], v[160:163], 0
	v_mfma_f32_16x16x32_bf16 v[88:91], v[172:175], v[148:151], 0
	v_mfma_f32_16x16x32_bf16 v[80:83], v[172:175], v[152:155], 0
	v_mfma_f32_16x16x32_bf16 v[76:79], v[172:175], v[156:159], 0
	v_mfma_f32_16x16x32_bf16 v[72:75], v[172:175], v[160:163], 0
	v_mfma_f32_16x16x32_bf16 v[68:71], v[176:179], v[148:151], 0
	v_mfma_f32_16x16x32_bf16 v[64:67], v[176:179], v[152:155], 0
	v_mfma_f32_16x16x32_bf16 v[60:63], v[176:179], v[156:159], 0
	v_mfma_f32_16x16x32_bf16 v[56:59], v[176:179], v[160:163], 0
	v_add_u32_e32 v176, v142, v143
	v_add_u32_e32 v132, v142, v141
	ds_read_b128 v[164:167], v176 offset:32768
	ds_read_b128 v[168:171], v176 offset:34816
	ds_read_b128 v[172:175], v176 offset:36864
	ds_read_b128 v[176:179], v176 offset:38912
	ds_read_b128 v[198:201], v132 offset:0
	ds_read_b128 v[202:205], v132 offset:2048
	ds_read_b128 v[206:209], v132 offset:4096
	ds_read_b128 v[210:213], v132 offset:6144
	s_waitcnt lgkmcnt(8)
	v_mfma_f32_16x16x32_bf16 v[52:55], v[180:183], v[148:151], 0
	v_mfma_f32_16x16x32_bf16 v[48:51], v[180:183], v[152:155], 0
	v_mfma_f32_16x16x32_bf16 v[44:47], v[180:183], v[156:159], 0
	v_mfma_f32_16x16x32_bf16 v[40:43], v[180:183], v[160:163], 0
	v_mfma_f32_16x16x32_bf16 v[36:39], v[186:189], v[148:151], 0
	v_mfma_f32_16x16x32_bf16 v[32:35], v[186:189], v[152:155], 0
	v_mfma_f32_16x16x32_bf16 v[28:31], v[186:189], v[156:159], 0
	v_mfma_f32_16x16x32_bf16 v[24:27], v[186:189], v[160:163], 0
	v_mfma_f32_16x16x32_bf16 v[20:23], v[190:193], v[148:151], 0
	v_mfma_f32_16x16x32_bf16 v[16:19], v[190:193], v[152:155], 0
	v_mfma_f32_16x16x32_bf16 v[12:15], v[190:193], v[156:159], 0
	v_mfma_f32_16x16x32_bf16 v[8:11], v[190:193], v[160:163], 0
	v_mfma_f32_16x16x32_bf16 v[4:7], v[194:197], v[148:151], 0
	v_mfma_f32_16x16x32_bf16 v[0:3], v[194:197], v[152:155], 0
	v_mfma_f32_16x16x32_bf16 v[92:95], v[194:197], v[156:159], 0
	v_mfma_f32_16x16x32_bf16 v[84:87], v[194:197], v[160:163], 0
	ds_read_b128 v[148:151], v132 offset:8192
	ds_read_b128 v[152:155], v132 offset:10240
	ds_read_b128 v[156:159], v132 offset:12288
	ds_read_b128 v[160:163], v132 offset:14336
	s_waitcnt lgkmcnt(4)
	v_mfma_f32_16x16x32_bf16 v[124:127], v[198:201], v[164:167], v[124:127]
	v_mfma_f32_16x16x32_bf16 v[120:123], v[198:201], v[168:171], v[120:123]
	v_mfma_f32_16x16x32_bf16 v[116:119], v[198:201], v[172:175], v[116:119]
	v_mfma_f32_16x16x32_bf16 v[112:115], v[198:201], v[176:179], v[112:115]
	v_mfma_f32_16x16x32_bf16 v[108:111], v[202:205], v[164:167], v[108:111]
	v_mfma_f32_16x16x32_bf16 v[104:107], v[202:205], v[168:171], v[104:107]
	v_mfma_f32_16x16x32_bf16 v[100:103], v[202:205], v[172:175], v[100:103]
	v_mfma_f32_16x16x32_bf16 v[96:99], v[202:205], v[176:179], v[96:99]
	v_mfma_f32_16x16x32_bf16 v[88:91], v[206:209], v[164:167], v[88:91]
	v_mfma_f32_16x16x32_bf16 v[80:83], v[206:209], v[168:171], v[80:83]
	v_mfma_f32_16x16x32_bf16 v[76:79], v[206:209], v[172:175], v[76:79]
	v_mfma_f32_16x16x32_bf16 v[72:75], v[206:209], v[176:179], v[72:75]
	v_mfma_f32_16x16x32_bf16 v[68:71], v[210:213], v[164:167], v[68:71]
	v_mfma_f32_16x16x32_bf16 v[64:67], v[210:213], v[168:171], v[64:67]
	v_mfma_f32_16x16x32_bf16 v[60:63], v[210:213], v[172:175], v[60:63]
	v_mfma_f32_16x16x32_bf16 v[56:59], v[210:213], v[176:179], v[56:59]
	s_waitcnt lgkmcnt(0)
	v_mfma_f32_16x16x32_bf16 v[52:55], v[148:151], v[164:167], v[52:55]
	s_waitcnt vmcnt(0)
	s_barrier
	v_add3_u32 v194, v146, v143, s99
	v_add3_u32 v132, v146, v141, s99
	v_mfma_f32_16x16x32_bf16 v[48:51], v[148:151], v[168:171], v[48:51]
	ds_read_b128 v[180:183], v194 offset:32768
	ds_read_b128 v[186:189], v194 offset:34816
	v_mfma_f32_16x16x32_bf16 v[44:47], v[148:151], v[172:175], v[44:47]
	ds_read_b128 v[190:193], v194 offset:36864
	ds_read_b128 v[194:197], v194 offset:38912
	v_mfma_f32_16x16x32_bf16 v[40:43], v[148:151], v[176:179], v[40:43]
	ds_read_b128 v[198:201], v132 offset:0
	ds_read_b128 v[202:205], v132 offset:2048
	v_mfma_f32_16x16x32_bf16 v[36:39], v[152:155], v[164:167], v[36:39]
	ds_read_b128 v[206:209], v132 offset:4096
	ds_read_b128 v[210:213], v132 offset:6144
	s_mov_b32 m0, s8
	v_mfma_f32_16x16x32_bf16 v[32:35], v[152:155], v[168:171], v[32:35]
	global_load_lds_dwordx4 v[128:129], off
	v_lshl_add_u64 v[128:129], v[128:129], 0, s[100:101]
	s_add_i32 m0, s8, 0x8000
	v_mfma_f32_16x16x32_bf16 v[28:31], v[152:155], v[172:175], v[28:31]
	global_load_lds_dwordx4 v[234:235], off
	v_lshl_add_u64 v[234:235], v[234:235], 0, s[100:101]
	s_mov_b32 m0, s11
	v_mfma_f32_16x16x32_bf16 v[24:27], v[152:155], v[176:179], v[24:27]
	global_load_lds_dwordx4 v[130:131], off
	v_lshl_add_u64 v[130:131], v[130:131], 0, s[100:101]
	s_add_i32 m0, s11, 0x8000
	v_mfma_f32_16x16x32_bf16 v[20:23], v[156:159], v[164:167], v[20:23]
	global_load_lds_dwordx4 v[236:237], off
	v_lshl_add_u64 v[236:237], v[236:237], 0, s[100:101]
	s_mov_b32 m0, s12
	v_mfma_f32_16x16x32_bf16 v[16:19], v[156:159], v[168:171], v[16:19]
	global_load_lds_dwordx4 v[134:135], off
	v_lshl_add_u64 v[134:135], v[134:135], 0, s[100:101]
	s_add_i32 m0, s12, 0x8000
	v_mfma_f32_16x16x32_bf16 v[12:15], v[156:159], v[172:175], v[12:15]
	global_load_lds_dwordx4 v[238:239], off
	v_lshl_add_u64 v[238:239], v[238:239], 0, s[100:101]
	s_mov_b32 m0, s13
	v_mfma_f32_16x16x32_bf16 v[8:11], v[156:159], v[176:179], v[8:11]
	global_load_lds_dwordx4 v[136:137], off
	v_lshl_add_u64 v[136:137], v[136:137], 0, s[100:101]
	s_add_i32 m0, s13, 0x8000
	v_mfma_f32_16x16x32_bf16 v[4:7], v[160:163], v[164:167], v[4:7]
	global_load_lds_dwordx4 v[240:241], off
	v_lshl_add_u64 v[240:241], v[240:241], 0, s[100:101]
	v_mfma_f32_16x16x32_bf16 v[0:3], v[160:163], v[168:171], v[0:3]
	v_mfma_f32_16x16x32_bf16 v[92:95], v[160:163], v[172:175], v[92:95]
	v_mfma_f32_16x16x32_bf16 v[84:87], v[160:163], v[176:179], v[84:87]
	ds_read_b128 v[148:151], v132 offset:8192
	ds_read_b128 v[152:155], v132 offset:10240
	ds_read_b128 v[156:159], v132 offset:12288
	ds_read_b128 v[160:163], v132 offset:14336
	s_waitcnt lgkmcnt(4)
	v_mfma_f32_16x16x32_bf16 v[124:127], v[198:201], v[180:183], v[124:127]
	v_mfma_f32_16x16x32_bf16 v[120:123], v[198:201], v[186:189], v[120:123]
	v_mfma_f32_16x16x32_bf16 v[116:119], v[198:201], v[190:193], v[116:119]
	v_mfma_f32_16x16x32_bf16 v[112:115], v[198:201], v[194:197], v[112:115]
	v_mfma_f32_16x16x32_bf16 v[108:111], v[202:205], v[180:183], v[108:111]
	v_mfma_f32_16x16x32_bf16 v[104:107], v[202:205], v[186:189], v[104:107]
	v_mfma_f32_16x16x32_bf16 v[100:103], v[202:205], v[190:193], v[100:103]
	v_mfma_f32_16x16x32_bf16 v[96:99], v[202:205], v[194:197], v[96:99]
	v_mfma_f32_16x16x32_bf16 v[88:91], v[206:209], v[180:183], v[88:91]
	v_mfma_f32_16x16x32_bf16 v[80:83], v[206:209], v[186:189], v[80:83]
	v_mfma_f32_16x16x32_bf16 v[76:79], v[206:209], v[190:193], v[76:79]
	v_mfma_f32_16x16x32_bf16 v[72:75], v[206:209], v[194:197], v[72:75]
	v_mfma_f32_16x16x32_bf16 v[68:71], v[210:213], v[180:183], v[68:71]
	v_mfma_f32_16x16x32_bf16 v[64:67], v[210:213], v[186:189], v[64:67]
	v_mfma_f32_16x16x32_bf16 v[60:63], v[210:213], v[190:193], v[60:63]
	v_mfma_f32_16x16x32_bf16 v[56:59], v[210:213], v[194:197], v[56:59]
	v_add3_u32 v210, v142, v143, s99
	v_add3_u32 v132, v142, v141, s99
	ds_read_b128 v[198:201], v210 offset:32768
	ds_read_b128 v[202:205], v210 offset:34816
	ds_read_b128 v[206:209], v210 offset:36864
	ds_read_b128 v[210:213], v210 offset:38912
	ds_read_b128 v[164:167], v132 offset:0
	ds_read_b128 v[168:171], v132 offset:2048
	ds_read_b128 v[172:175], v132 offset:4096
	ds_read_b128 v[176:179], v132 offset:6144
	s_waitcnt lgkmcnt(8)
	v_mfma_f32_16x16x32_bf16 v[52:55], v[148:151], v[180:183], v[52:55]
	v_mfma_f32_16x16x32_bf16 v[48:51], v[148:151], v[186:189], v[48:51]
	v_mfma_f32_16x16x32_bf16 v[44:47], v[148:151], v[190:193], v[44:47]
	v_mfma_f32_16x16x32_bf16 v[40:43], v[148:151], v[194:197], v[40:43]
	v_mfma_f32_16x16x32_bf16 v[36:39], v[152:155], v[180:183], v[36:39]
	v_mfma_f32_16x16x32_bf16 v[32:35], v[152:155], v[186:189], v[32:35]
	v_mfma_f32_16x16x32_bf16 v[28:31], v[152:155], v[190:193], v[28:31]
	v_mfma_f32_16x16x32_bf16 v[24:27], v[152:155], v[194:197], v[24:27]
	v_mfma_f32_16x16x32_bf16 v[20:23], v[156:159], v[180:183], v[20:23]
	v_mfma_f32_16x16x32_bf16 v[16:19], v[156:159], v[186:189], v[16:19]
	v_mfma_f32_16x16x32_bf16 v[12:15], v[156:159], v[190:193], v[12:15]
	v_mfma_f32_16x16x32_bf16 v[8:11], v[156:159], v[194:197], v[8:11]
	v_mfma_f32_16x16x32_bf16 v[4:7], v[160:163], v[180:183], v[4:7]
	v_mfma_f32_16x16x32_bf16 v[0:3], v[160:163], v[186:189], v[0:3]
	v_mfma_f32_16x16x32_bf16 v[92:95], v[160:163], v[190:193], v[92:95]
	v_mfma_f32_16x16x32_bf16 v[84:87], v[160:163], v[194:197], v[84:87]
	ds_read_b128 v[180:183], v132 offset:8192
	ds_read_b128 v[186:189], v132 offset:10240
	ds_read_b128 v[190:193], v132 offset:12288
	ds_read_b128 v[194:197], v132 offset:14336
	s_waitcnt lgkmcnt(4)
	v_mfma_f32_16x16x32_bf16 v[124:127], v[164:167], v[198:201], v[124:127]
	v_mfma_f32_16x16x32_bf16 v[120:123], v[164:167], v[202:205], v[120:123]
	v_mfma_f32_16x16x32_bf16 v[116:119], v[164:167], v[206:209], v[116:119]
	v_mfma_f32_16x16x32_bf16 v[112:115], v[164:167], v[210:213], v[112:115]
	v_mfma_f32_16x16x32_bf16 v[108:111], v[168:171], v[198:201], v[108:111]
	v_mfma_f32_16x16x32_bf16 v[104:107], v[168:171], v[202:205], v[104:107]
	v_mfma_f32_16x16x32_bf16 v[100:103], v[168:171], v[206:209], v[100:103]
	v_mfma_f32_16x16x32_bf16 v[96:99], v[168:171], v[210:213], v[96:99]
	v_mfma_f32_16x16x32_bf16 v[88:91], v[172:175], v[198:201], v[88:91]
	v_mfma_f32_16x16x32_bf16 v[80:83], v[172:175], v[202:205], v[80:83]
	v_mfma_f32_16x16x32_bf16 v[76:79], v[172:175], v[206:209], v[76:79]
	v_mfma_f32_16x16x32_bf16 v[72:75], v[172:175], v[210:213], v[72:75]
	v_mfma_f32_16x16x32_bf16 v[68:71], v[176:179], v[198:201], v[68:71]
	v_mfma_f32_16x16x32_bf16 v[64:67], v[176:179], v[202:205], v[64:67]
	v_mfma_f32_16x16x32_bf16 v[60:63], v[176:179], v[206:209], v[60:63]
	v_mfma_f32_16x16x32_bf16 v[56:59], v[176:179], v[210:213], v[56:59]
	s_waitcnt lgkmcnt(0)
	v_mfma_f32_16x16x32_bf16 v[52:55], v[180:183], v[198:201], v[52:55]
	s_waitcnt vmcnt(0)
	s_barrier
	v_add_u32_e32 v160, v146, v143
	v_add_u32_e32 v132, v146, v141
	v_mfma_f32_16x16x32_bf16 v[48:51], v[180:183], v[202:205], v[48:51]
	ds_read_b128 v[148:151], v160 offset:32768
	ds_read_b128 v[152:155], v160 offset:34816
	v_mfma_f32_16x16x32_bf16 v[44:47], v[180:183], v[206:209], v[44:47]
	ds_read_b128 v[156:159], v160 offset:36864
	ds_read_b128 v[160:163], v160 offset:38912
	v_mfma_f32_16x16x32_bf16 v[40:43], v[180:183], v[210:213], v[40:43]
	ds_read_b128 v[164:167], v132 offset:0
	ds_read_b128 v[168:171], v132 offset:2048
	v_mfma_f32_16x16x32_bf16 v[36:39], v[186:189], v[198:201], v[36:39]
	ds_read_b128 v[172:175], v132 offset:4096
	ds_read_b128 v[176:179], v132 offset:6144
	s_add_i32 m0, s8, 0x10000
	v_mfma_f32_16x16x32_bf16 v[32:35], v[186:189], v[202:205], v[32:35]
	global_load_lds_dwordx4 v[128:129], off
	v_lshl_add_u64 v[128:129], v[128:129], 0, s[100:101]
	s_add_i32 m0, s8, 0x18000
	v_mfma_f32_16x16x32_bf16 v[28:31], v[186:189], v[206:209], v[28:31]
	global_load_lds_dwordx4 v[234:235], off
	v_lshl_add_u64 v[234:235], v[234:235], 0, s[100:101]
	s_add_i32 m0, s11, 0x10000
	v_mfma_f32_16x16x32_bf16 v[24:27], v[186:189], v[210:213], v[24:27]
	global_load_lds_dwordx4 v[130:131], off
	v_lshl_add_u64 v[130:131], v[130:131], 0, s[100:101]
	s_add_i32 m0, s11, 0x18000
	v_mfma_f32_16x16x32_bf16 v[20:23], v[190:193], v[198:201], v[20:23]
	global_load_lds_dwordx4 v[236:237], off
	v_lshl_add_u64 v[236:237], v[236:237], 0, s[100:101]
	s_add_i32 m0, s12, 0x10000
	v_mfma_f32_16x16x32_bf16 v[16:19], v[190:193], v[202:205], v[16:19]
	global_load_lds_dwordx4 v[134:135], off
	v_lshl_add_u64 v[134:135], v[134:135], 0, s[100:101]
	s_add_i32 m0, s12, 0x18000
	v_mfma_f32_16x16x32_bf16 v[12:15], v[190:193], v[206:209], v[12:15]
	global_load_lds_dwordx4 v[238:239], off
	v_lshl_add_u64 v[238:239], v[238:239], 0, s[100:101]
	s_add_i32 m0, s13, 0x10000
	v_mfma_f32_16x16x32_bf16 v[8:11], v[190:193], v[210:213], v[8:11]
	global_load_lds_dwordx4 v[136:137], off
	v_lshl_add_u64 v[136:137], v[136:137], 0, s[100:101]
	s_add_i32 m0, s13, 0x18000
	v_mfma_f32_16x16x32_bf16 v[4:7], v[194:197], v[198:201], v[4:7]
	global_load_lds_dwordx4 v[240:241], off
	v_lshl_add_u64 v[240:241], v[240:241], 0, s[100:101]
	v_mfma_f32_16x16x32_bf16 v[0:3], v[194:197], v[202:205], v[0:3]
	v_mfma_f32_16x16x32_bf16 v[92:95], v[194:197], v[206:209], v[92:95]
	v_mfma_f32_16x16x32_bf16 v[84:87], v[194:197], v[210:213], v[84:87]
	s_movk_i32 s2, 0x100
.Lg_out_loop:
	s_cmpk_lg_i32 s2, 0x300
	s_cbranch_scc1 .Lg_out_norebase
	s_add_u32 s42, s31, 0x380
	s_addc_u32 s43, s34, 0
	v_mov_b32_e32 v243, 0
	v_lshl_or_b32 v242, v139, 11, v138
	v_lshl_add_u64 v[234:235], s[42:43], 0, v[242:243]
	v_lshl_or_b32 v242, v140, 11, v138
	v_lshl_add_u64 v[236:237], s[42:43], 0, v[242:243]
	v_lshl_or_b32 v242, v144, 11, v138
	v_lshl_add_u64 v[238:239], s[42:43], 0, v[242:243]
	v_lshl_or_b32 v242, v145, 11, v138
	v_lshl_add_u64 v[240:241], s[42:43], 0, v[242:243]
.Lg_out_norebase:
	ds_read_b128 v[180:183], v132 offset:8192
	ds_read_b128 v[186:189], v132 offset:10240
	ds_read_b128 v[190:193], v132 offset:12288
	ds_read_b128 v[194:197], v132 offset:14336
	s_waitcnt lgkmcnt(4)
	v_mfma_f32_16x16x32_bf16 v[124:127], v[164:167], v[148:151], v[124:127]
	v_mfma_f32_16x16x32_bf16 v[120:123], v[164:167], v[152:155], v[120:123]
	v_mfma_f32_16x16x32_bf16 v[116:119], v[164:167], v[156:159], v[116:119]
	v_mfma_f32_16x16x32_bf16 v[112:115], v[164:167], v[160:163], v[112:115]
	v_mfma_f32_16x16x32_bf16 v[108:111], v[168:171], v[148:151], v[108:111]
	v_mfma_f32_16x16x32_bf16 v[104:107], v[168:171], v[152:155], v[104:107]
	v_mfma_f32_16x16x32_bf16 v[100:103], v[168:171], v[156:159], v[100:103]
	v_mfma_f32_16x16x32_bf16 v[96:99], v[168:171], v[160:163], v[96:99]
	v_mfma_f32_16x16x32_bf16 v[88:91], v[172:175], v[148:151], v[88:91]
	v_mfma_f32_16x16x32_bf16 v[80:83], v[172:175], v[152:155], v[80:83]
	v_mfma_f32_16x16x32_bf16 v[76:79], v[172:175], v[156:159], v[76:79]
	v_mfma_f32_16x16x32_bf16 v[72:75], v[172:175], v[160:163], v[72:75]
	v_mfma_f32_16x16x32_bf16 v[68:71], v[176:179], v[148:151], v[68:71]
	v_mfma_f32_16x16x32_bf16 v[64:67], v[176:179], v[152:155], v[64:67]
	v_mfma_f32_16x16x32_bf16 v[60:63], v[176:179], v[156:159], v[60:63]
	v_mfma_f32_16x16x32_bf16 v[56:59], v[176:179], v[160:163], v[56:59]
	v_add_u32_e32 v176, v142, v143
	v_add_u32_e32 v132, v142, v141
	ds_read_b128 v[164:167], v176 offset:32768
	ds_read_b128 v[168:171], v176 offset:34816
	ds_read_b128 v[172:175], v176 offset:36864
	ds_read_b128 v[176:179], v176 offset:38912
	ds_read_b128 v[198:201], v132 offset:0
	ds_read_b128 v[202:205], v132 offset:2048
	ds_read_b128 v[206:209], v132 offset:4096
	ds_read_b128 v[210:213], v132 offset:6144
	s_waitcnt lgkmcnt(8)
	v_mfma_f32_16x16x32_bf16 v[52:55], v[180:183], v[148:151], v[52:55]
	v_mfma_f32_16x16x32_bf16 v[48:51], v[180:183], v[152:155], v[48:51]
	v_mfma_f32_16x16x32_bf16 v[44:47], v[180:183], v[156:159], v[44:47]
	v_mfma_f32_16x16x32_bf16 v[40:43], v[180:183], v[160:163], v[40:43]
	v_mfma_f32_16x16x32_bf16 v[36:39], v[186:189], v[148:151], v[36:39]
	v_mfma_f32_16x16x32_bf16 v[32:35], v[186:189], v[152:155], v[32:35]
	v_mfma_f32_16x16x32_bf16 v[28:31], v[186:189], v[156:159], v[28:31]
	v_mfma_f32_16x16x32_bf16 v[24:27], v[186:189], v[160:163], v[24:27]
	v_mfma_f32_16x16x32_bf16 v[20:23], v[190:193], v[148:151], v[20:23]
	v_mfma_f32_16x16x32_bf16 v[16:19], v[190:193], v[152:155], v[16:19]
	v_mfma_f32_16x16x32_bf16 v[12:15], v[190:193], v[156:159], v[12:15]
	v_mfma_f32_16x16x32_bf16 v[8:11], v[190:193], v[160:163], v[8:11]
	v_mfma_f32_16x16x32_bf16 v[4:7], v[194:197], v[148:151], v[4:7]
	v_mfma_f32_16x16x32_bf16 v[0:3], v[194:197], v[152:155], v[0:3]
	v_mfma_f32_16x16x32_bf16 v[92:95], v[194:197], v[156:159], v[92:95]
	v_mfma_f32_16x16x32_bf16 v[84:87], v[194:197], v[160:163], v[84:87]
	ds_read_b128 v[148:151], v132 offset:8192
	ds_read_b128 v[152:155], v132 offset:10240
	ds_read_b128 v[156:159], v132 offset:12288
	ds_read_b128 v[160:163], v132 offset:14336
	s_waitcnt lgkmcnt(4)
	v_mfma_f32_16x16x32_bf16 v[124:127], v[198:201], v[164:167], v[124:127]
	v_mfma_f32_16x16x32_bf16 v[120:123], v[198:201], v[168:171], v[120:123]
	v_mfma_f32_16x16x32_bf16 v[116:119], v[198:201], v[172:175], v[116:119]
	v_mfma_f32_16x16x32_bf16 v[112:115], v[198:201], v[176:179], v[112:115]
	v_mfma_f32_16x16x32_bf16 v[108:111], v[202:205], v[164:167], v[108:111]
	v_mfma_f32_16x16x32_bf16 v[104:107], v[202:205], v[168:171], v[104:107]
	v_mfma_f32_16x16x32_bf16 v[100:103], v[202:205], v[172:175], v[100:103]
	v_mfma_f32_16x16x32_bf16 v[96:99], v[202:205], v[176:179], v[96:99]
	v_mfma_f32_16x16x32_bf16 v[88:91], v[206:209], v[164:167], v[88:91]
	v_mfma_f32_16x16x32_bf16 v[80:83], v[206:209], v[168:171], v[80:83]
	v_mfma_f32_16x16x32_bf16 v[76:79], v[206:209], v[172:175], v[76:79]
	v_mfma_f32_16x16x32_bf16 v[72:75], v[206:209], v[176:179], v[72:75]
	v_mfma_f32_16x16x32_bf16 v[68:71], v[210:213], v[164:167], v[68:71]
	v_mfma_f32_16x16x32_bf16 v[64:67], v[210:213], v[168:171], v[64:67]
	v_mfma_f32_16x16x32_bf16 v[60:63], v[210:213], v[172:175], v[60:63]
	v_mfma_f32_16x16x32_bf16 v[56:59], v[210:213], v[176:179], v[56:59]
	s_waitcnt lgkmcnt(0)
	v_mfma_f32_16x16x32_bf16 v[52:55], v[148:151], v[164:167], v[52:55]
	s_waitcnt vmcnt(0)
	s_barrier
	v_add3_u32 v194, v146, v143, s99
	v_add3_u32 v132, v146, v141, s99
	v_mfma_f32_16x16x32_bf16 v[48:51], v[148:151], v[168:171], v[48:51]
	ds_read_b128 v[180:183], v194 offset:32768
	ds_read_b128 v[186:189], v194 offset:34816
	v_mfma_f32_16x16x32_bf16 v[44:47], v[148:151], v[172:175], v[44:47]
	ds_read_b128 v[190:193], v194 offset:36864
	ds_read_b128 v[194:197], v194 offset:38912
	v_mfma_f32_16x16x32_bf16 v[40:43], v[148:151], v[176:179], v[40:43]
	ds_read_b128 v[198:201], v132 offset:0
	ds_read_b128 v[202:205], v132 offset:2048
	v_mfma_f32_16x16x32_bf16 v[36:39], v[152:155], v[164:167], v[36:39]
	ds_read_b128 v[206:209], v132 offset:4096
	ds_read_b128 v[210:213], v132 offset:6144
	s_mov_b32 m0, s8
	v_mfma_f32_16x16x32_bf16 v[32:35], v[152:155], v[168:171], v[32:35]
	global_load_lds_dwordx4 v[128:129], off
	v_lshl_add_u64 v[128:129], v[128:129], 0, s[100:101]
	s_add_i32 m0, s8, 0x8000
	v_mfma_f32_16x16x32_bf16 v[28:31], v[152:155], v[172:175], v[28:31]
	global_load_lds_dwordx4 v[234:235], off
	v_lshl_add_u64 v[234:235], v[234:235], 0, s[100:101]
	s_mov_b32 m0, s11
	v_mfma_f32_16x16x32_bf16 v[24:27], v[152:155], v[176:179], v[24:27]
	global_load_lds_dwordx4 v[130:131], off
	v_lshl_add_u64 v[130:131], v[130:131], 0, s[100:101]
	s_add_i32 m0, s11, 0x8000
	v_mfma_f32_16x16x32_bf16 v[20:23], v[156:159], v[164:167], v[20:23]
	global_load_lds_dwordx4 v[236:237], off
	v_lshl_add_u64 v[236:237], v[236:237], 0, s[100:101]
	s_mov_b32 m0, s12
	v_mfma_f32_16x16x32_bf16 v[16:19], v[156:159], v[168:171], v[16:19]
	global_load_lds_dwordx4 v[134:135], off
	v_lshl_add_u64 v[134:135], v[134:135], 0, s[100:101]
	s_add_i32 m0, s12, 0x8000
	v_mfma_f32_16x16x32_bf16 v[12:15], v[156:159], v[172:175], v[12:15]
	global_load_lds_dwordx4 v[238:239], off
	v_lshl_add_u64 v[238:239], v[238:239], 0, s[100:101]
	s_mov_b32 m0, s13
	v_mfma_f32_16x16x32_bf16 v[8:11], v[156:159], v[176:179], v[8:11]
	global_load_lds_dwordx4 v[136:137], off
	v_lshl_add_u64 v[136:137], v[136:137], 0, s[100:101]
	s_add_i32 m0, s13, 0x8000
	v_mfma_f32_16x16x32_bf16 v[4:7], v[160:163], v[164:167], v[4:7]
	global_load_lds_dwordx4 v[240:241], off
	v_lshl_add_u64 v[240:241], v[240:241], 0, s[100:101]
	v_mfma_f32_16x16x32_bf16 v[0:3], v[160:163], v[168:171], v[0:3]
	v_mfma_f32_16x16x32_bf16 v[92:95], v[160:163], v[172:175], v[92:95]
	v_mfma_f32_16x16x32_bf16 v[84:87], v[160:163], v[176:179], v[84:87]
	ds_read_b128 v[148:151], v132 offset:8192
	ds_read_b128 v[152:155], v132 offset:10240
	ds_read_b128 v[156:159], v132 offset:12288
	ds_read_b128 v[160:163], v132 offset:14336
	s_waitcnt lgkmcnt(4)
	v_mfma_f32_16x16x32_bf16 v[124:127], v[198:201], v[180:183], v[124:127]
	v_mfma_f32_16x16x32_bf16 v[120:123], v[198:201], v[186:189], v[120:123]
	v_mfma_f32_16x16x32_bf16 v[116:119], v[198:201], v[190:193], v[116:119]
	v_mfma_f32_16x16x32_bf16 v[112:115], v[198:201], v[194:197], v[112:115]
	v_mfma_f32_16x16x32_bf16 v[108:111], v[202:205], v[180:183], v[108:111]
	v_mfma_f32_16x16x32_bf16 v[104:107], v[202:205], v[186:189], v[104:107]
	v_mfma_f32_16x16x32_bf16 v[100:103], v[202:205], v[190:193], v[100:103]
	v_mfma_f32_16x16x32_bf16 v[96:99], v[202:205], v[194:197], v[96:99]
	v_mfma_f32_16x16x32_bf16 v[88:91], v[206:209], v[180:183], v[88:91]
	v_mfma_f32_16x16x32_bf16 v[80:83], v[206:209], v[186:189], v[80:83]
	v_mfma_f32_16x16x32_bf16 v[76:79], v[206:209], v[190:193], v[76:79]
	v_mfma_f32_16x16x32_bf16 v[72:75], v[206:209], v[194:197], v[72:75]
	v_mfma_f32_16x16x32_bf16 v[68:71], v[210:213], v[180:183], v[68:71]
	v_mfma_f32_16x16x32_bf16 v[64:67], v[210:213], v[186:189], v[64:67]
	v_mfma_f32_16x16x32_bf16 v[60:63], v[210:213], v[190:193], v[60:63]
	v_mfma_f32_16x16x32_bf16 v[56:59], v[210:213], v[194:197], v[56:59]
	v_add3_u32 v210, v142, v143, s99
	v_add3_u32 v132, v142, v141, s99
	ds_read_b128 v[198:201], v210 offset:32768
	ds_read_b128 v[202:205], v210 offset:34816
	ds_read_b128 v[206:209], v210 offset:36864
	ds_read_b128 v[210:213], v210 offset:38912
	ds_read_b128 v[164:167], v132 offset:0
	ds_read_b128 v[168:171], v132 offset:2048
	ds_read_b128 v[172:175], v132 offset:4096
	ds_read_b128 v[176:179], v132 offset:6144
	s_waitcnt lgkmcnt(8)
	v_mfma_f32_16x16x32_bf16 v[52:55], v[148:151], v[180:183], v[52:55]
	v_mfma_f32_16x16x32_bf16 v[48:51], v[148:151], v[186:189], v[48:51]
	v_mfma_f32_16x16x32_bf16 v[44:47], v[148:151], v[190:193], v[44:47]
	v_mfma_f32_16x16x32_bf16 v[40:43], v[148:151], v[194:197], v[40:43]
	v_mfma_f32_16x16x32_bf16 v[36:39], v[152:155], v[180:183], v[36:39]
	v_mfma_f32_16x16x32_bf16 v[32:35], v[152:155], v[186:189], v[32:35]
	v_mfma_f32_16x16x32_bf16 v[28:31], v[152:155], v[190:193], v[28:31]
	v_mfma_f32_16x16x32_bf16 v[24:27], v[152:155], v[194:197], v[24:27]
	v_mfma_f32_16x16x32_bf16 v[20:23], v[156:159], v[180:183], v[20:23]
	v_mfma_f32_16x16x32_bf16 v[16:19], v[156:159], v[186:189], v[16:19]
	v_mfma_f32_16x16x32_bf16 v[12:15], v[156:159], v[190:193], v[12:15]
	v_mfma_f32_16x16x32_bf16 v[8:11], v[156:159], v[194:197], v[8:11]
	v_mfma_f32_16x16x32_bf16 v[4:7], v[160:163], v[180:183], v[4:7]
	v_mfma_f32_16x16x32_bf16 v[0:3], v[160:163], v[186:189], v[0:3]
	v_mfma_f32_16x16x32_bf16 v[92:95], v[160:163], v[190:193], v[92:95]
	v_mfma_f32_16x16x32_bf16 v[84:87], v[160:163], v[194:197], v[84:87]
	ds_read_b128 v[180:183], v132 offset:8192
	ds_read_b128 v[186:189], v132 offset:10240
	ds_read_b128 v[190:193], v132 offset:12288
	ds_read_b128 v[194:197], v132 offset:14336
	s_waitcnt lgkmcnt(4)
	v_mfma_f32_16x16x32_bf16 v[124:127], v[164:167], v[198:201], v[124:127]
	v_mfma_f32_16x16x32_bf16 v[120:123], v[164:167], v[202:205], v[120:123]
	v_mfma_f32_16x16x32_bf16 v[116:119], v[164:167], v[206:209], v[116:119]
	v_mfma_f32_16x16x32_bf16 v[112:115], v[164:167], v[210:213], v[112:115]
	v_mfma_f32_16x16x32_bf16 v[108:111], v[168:171], v[198:201], v[108:111]
	v_mfma_f32_16x16x32_bf16 v[104:107], v[168:171], v[202:205], v[104:107]
	v_mfma_f32_16x16x32_bf16 v[100:103], v[168:171], v[206:209], v[100:103]
	v_mfma_f32_16x16x32_bf16 v[96:99], v[168:171], v[210:213], v[96:99]
	v_mfma_f32_16x16x32_bf16 v[88:91], v[172:175], v[198:201], v[88:91]
	v_mfma_f32_16x16x32_bf16 v[80:83], v[172:175], v[202:205], v[80:83]
	v_mfma_f32_16x16x32_bf16 v[76:79], v[172:175], v[206:209], v[76:79]
	v_mfma_f32_16x16x32_bf16 v[72:75], v[172:175], v[210:213], v[72:75]
	v_mfma_f32_16x16x32_bf16 v[68:71], v[176:179], v[198:201], v[68:71]
	v_mfma_f32_16x16x32_bf16 v[64:67], v[176:179], v[202:205], v[64:67]
	v_mfma_f32_16x16x32_bf16 v[60:63], v[176:179], v[206:209], v[60:63]
	v_mfma_f32_16x16x32_bf16 v[56:59], v[176:179], v[210:213], v[56:59]
	s_waitcnt lgkmcnt(0)
	v_mfma_f32_16x16x32_bf16 v[52:55], v[180:183], v[198:201], v[52:55]
	s_waitcnt vmcnt(0)
	s_barrier
	v_add_u32_e32 v160, v146, v143
	v_add_u32_e32 v132, v146, v141
	v_mfma_f32_16x16x32_bf16 v[48:51], v[180:183], v[202:205], v[48:51]
	ds_read_b128 v[148:151], v160 offset:32768
	ds_read_b128 v[152:155], v160 offset:34816
	v_mfma_f32_16x16x32_bf16 v[44:47], v[180:183], v[206:209], v[44:47]
	ds_read_b128 v[156:159], v160 offset:36864
	ds_read_b128 v[160:163], v160 offset:38912
	v_mfma_f32_16x16x32_bf16 v[40:43], v[180:183], v[210:213], v[40:43]
	ds_read_b128 v[164:167], v132 offset:0
	ds_read_b128 v[168:171], v132 offset:2048
	v_mfma_f32_16x16x32_bf16 v[36:39], v[186:189], v[198:201], v[36:39]
	ds_read_b128 v[172:175], v132 offset:4096
	ds_read_b128 v[176:179], v132 offset:6144
	s_add_i32 m0, s8, 0x10000
	v_mfma_f32_16x16x32_bf16 v[32:35], v[186:189], v[202:205], v[32:35]
	global_load_lds_dwordx4 v[128:129], off
	v_lshl_add_u64 v[128:129], v[128:129], 0, s[100:101]
	s_add_i32 m0, s8, 0x18000
	v_mfma_f32_16x16x32_bf16 v[28:31], v[186:189], v[206:209], v[28:31]
	global_load_lds_dwordx4 v[234:235], off
	v_lshl_add_u64 v[234:235], v[234:235], 0, s[100:101]
	s_add_i32 m0, s11, 0x10000
	v_mfma_f32_16x16x32_bf16 v[24:27], v[186:189], v[210:213], v[24:27]
	global_load_lds_dwordx4 v[130:131], off
	v_lshl_add_u64 v[130:131], v[130:131], 0, s[100:101]
	s_add_i32 m0, s11, 0x18000
	v_mfma_f32_16x16x32_bf16 v[20:23], v[190:193], v[198:201], v[20:23]
	global_load_lds_dwordx4 v[236:237], off
	v_lshl_add_u64 v[236:237], v[236:237], 0, s[100:101]
	s_add_i32 m0, s12, 0x10000
	v_mfma_f32_16x16x32_bf16 v[16:19], v[190:193], v[202:205], v[16:19]
	global_load_lds_dwordx4 v[134:135], off
	v_lshl_add_u64 v[134:135], v[134:135], 0, s[100:101]
	s_add_i32 m0, s12, 0x18000
	v_mfma_f32_16x16x32_bf16 v[12:15], v[190:193], v[206:209], v[12:15]
	global_load_lds_dwordx4 v[238:239], off
	v_lshl_add_u64 v[238:239], v[238:239], 0, s[100:101]
	s_add_i32 m0, s13, 0x10000
	v_mfma_f32_16x16x32_bf16 v[8:11], v[190:193], v[210:213], v[8:11]
	global_load_lds_dwordx4 v[136:137], off
	v_lshl_add_u64 v[136:137], v[136:137], 0, s[100:101]
	s_add_i32 m0, s13, 0x18000
	v_mfma_f32_16x16x32_bf16 v[4:7], v[194:197], v[198:201], v[4:7]
	global_load_lds_dwordx4 v[240:241], off
	v_lshl_add_u64 v[240:241], v[240:241], 0, s[100:101]
	v_mfma_f32_16x16x32_bf16 v[0:3], v[194:197], v[202:205], v[0:3]
	v_mfma_f32_16x16x32_bf16 v[92:95], v[194:197], v[206:209], v[92:95]
	v_mfma_f32_16x16x32_bf16 v[84:87], v[194:197], v[210:213], v[84:87]
	s_add_u32 s2, s2, 0x100
	s_cmpk_lg_i32 s2, 0xb00
	s_cbranch_scc1 .Lg_out_loop
	ds_read_b128 v[180:183], v132 offset:8192
	ds_read_b128 v[186:189], v132 offset:10240
	ds_read_b128 v[190:193], v132 offset:12288
	ds_read_b128 v[194:197], v132 offset:14336
	s_waitcnt lgkmcnt(4)
	v_mfma_f32_16x16x32_bf16 v[124:127], v[164:167], v[148:151], v[124:127]
	v_mfma_f32_16x16x32_bf16 v[120:123], v[164:167], v[152:155], v[120:123]
	v_mfma_f32_16x16x32_bf16 v[116:119], v[164:167], v[156:159], v[116:119]
	v_mfma_f32_16x16x32_bf16 v[112:115], v[164:167], v[160:163], v[112:115]
	v_mfma_f32_16x16x32_bf16 v[108:111], v[168:171], v[148:151], v[108:111]
	v_mfma_f32_16x16x32_bf16 v[104:107], v[168:171], v[152:155], v[104:107]
	v_mfma_f32_16x16x32_bf16 v[100:103], v[168:171], v[156:159], v[100:103]
	v_mfma_f32_16x16x32_bf16 v[96:99], v[168:171], v[160:163], v[96:99]
	v_mfma_f32_16x16x32_bf16 v[88:91], v[172:175], v[148:151], v[88:91]
	v_mfma_f32_16x16x32_bf16 v[80:83], v[172:175], v[152:155], v[80:83]
	v_mfma_f32_16x16x32_bf16 v[76:79], v[172:175], v[156:159], v[76:79]
	v_mfma_f32_16x16x32_bf16 v[72:75], v[172:175], v[160:163], v[72:75]
	v_mfma_f32_16x16x32_bf16 v[68:71], v[176:179], v[148:151], v[68:71]
	v_mfma_f32_16x16x32_bf16 v[64:67], v[176:179], v[152:155], v[64:67]
	v_mfma_f32_16x16x32_bf16 v[60:63], v[176:179], v[156:159], v[60:63]
	v_mfma_f32_16x16x32_bf16 v[56:59], v[176:179], v[160:163], v[56:59]
	v_add_u32_e32 v176, v142, v143
	v_add_u32_e32 v132, v142, v141
	ds_read_b128 v[164:167], v176 offset:32768
	ds_read_b128 v[168:171], v176 offset:34816
	ds_read_b128 v[172:175], v176 offset:36864
	ds_read_b128 v[176:179], v176 offset:38912
	ds_read_b128 v[198:201], v132 offset:0
	ds_read_b128 v[202:205], v132 offset:2048
	ds_read_b128 v[206:209], v132 offset:4096
	ds_read_b128 v[210:213], v132 offset:6144
	s_waitcnt lgkmcnt(8)
	v_mfma_f32_16x16x32_bf16 v[52:55], v[180:183], v[148:151], v[52:55]
	v_mfma_f32_16x16x32_bf16 v[48:51], v[180:183], v[152:155], v[48:51]
	v_mfma_f32_16x16x32_bf16 v[44:47], v[180:183], v[156:159], v[44:47]
	v_mfma_f32_16x16x32_bf16 v[40:43], v[180:183], v[160:163], v[40:43]
	v_mfma_f32_16x16x32_bf16 v[36:39], v[186:189], v[148:151], v[36:39]
	v_mfma_f32_16x16x32_bf16 v[32:35], v[186:189], v[152:155], v[32:35]
	v_mfma_f32_16x16x32_bf16 v[28:31], v[186:189], v[156:159], v[28:31]
	v_mfma_f32_16x16x32_bf16 v[24:27], v[186:189], v[160:163], v[24:27]
	v_mfma_f32_16x16x32_bf16 v[20:23], v[190:193], v[148:151], v[20:23]
	v_mfma_f32_16x16x32_bf16 v[16:19], v[190:193], v[152:155], v[16:19]
	v_mfma_f32_16x16x32_bf16 v[12:15], v[190:193], v[156:159], v[12:15]
	v_mfma_f32_16x16x32_bf16 v[8:11], v[190:193], v[160:163], v[8:11]
	v_mfma_f32_16x16x32_bf16 v[4:7], v[194:197], v[148:151], v[4:7]
	v_mfma_f32_16x16x32_bf16 v[0:3], v[194:197], v[152:155], v[0:3]
	v_mfma_f32_16x16x32_bf16 v[92:95], v[194:197], v[156:159], v[92:95]
	v_mfma_f32_16x16x32_bf16 v[84:87], v[194:197], v[160:163], v[84:87]
	ds_read_b128 v[148:151], v132 offset:8192
	ds_read_b128 v[152:155], v132 offset:10240
	ds_read_b128 v[156:159], v132 offset:12288
	ds_read_b128 v[160:163], v132 offset:14336
	s_waitcnt lgkmcnt(4)
	v_mfma_f32_16x16x32_bf16 v[124:127], v[198:201], v[164:167], v[124:127]
	v_mfma_f32_16x16x32_bf16 v[120:123], v[198:201], v[168:171], v[120:123]
	v_mfma_f32_16x16x32_bf16 v[116:119], v[198:201], v[172:175], v[116:119]
	v_mfma_f32_16x16x32_bf16 v[112:115], v[198:201], v[176:179], v[112:115]
	v_mfma_f32_16x16x32_bf16 v[108:111], v[202:205], v[164:167], v[108:111]
	v_mfma_f32_16x16x32_bf16 v[104:107], v[202:205], v[168:171], v[104:107]
	v_mfma_f32_16x16x32_bf16 v[100:103], v[202:205], v[172:175], v[100:103]
	v_mfma_f32_16x16x32_bf16 v[96:99], v[202:205], v[176:179], v[96:99]
	v_mfma_f32_16x16x32_bf16 v[88:91], v[206:209], v[164:167], v[88:91]
	v_mfma_f32_16x16x32_bf16 v[80:83], v[206:209], v[168:171], v[80:83]
	v_mfma_f32_16x16x32_bf16 v[76:79], v[206:209], v[172:175], v[76:79]
	v_mfma_f32_16x16x32_bf16 v[72:75], v[206:209], v[176:179], v[72:75]
	v_mfma_f32_16x16x32_bf16 v[68:71], v[210:213], v[164:167], v[68:71]
	v_mfma_f32_16x16x32_bf16 v[64:67], v[210:213], v[168:171], v[64:67]
	v_mfma_f32_16x16x32_bf16 v[60:63], v[210:213], v[172:175], v[60:63]
	v_mfma_f32_16x16x32_bf16 v[56:59], v[210:213], v[176:179], v[56:59]
	s_waitcnt lgkmcnt(0)
	v_mfma_f32_16x16x32_bf16 v[52:55], v[148:151], v[164:167], v[52:55]
	s_waitcnt vmcnt(0)
	s_barrier
	v_mfma_f32_16x16x32_bf16 v[48:51], v[148:151], v[168:171], v[48:51]
	v_mfma_f32_16x16x32_bf16 v[44:47], v[148:151], v[172:175], v[44:47]
	v_mfma_f32_16x16x32_bf16 v[40:43], v[148:151], v[176:179], v[40:43]
	v_mfma_f32_16x16x32_bf16 v[36:39], v[152:155], v[164:167], v[36:39]
	v_mfma_f32_16x16x32_bf16 v[32:35], v[152:155], v[168:171], v[32:35]
	v_mfma_f32_16x16x32_bf16 v[28:31], v[152:155], v[172:175], v[28:31]
	v_mfma_f32_16x16x32_bf16 v[24:27], v[152:155], v[176:179], v[24:27]
	v_mfma_f32_16x16x32_bf16 v[20:23], v[156:159], v[164:167], v[20:23]
	v_mfma_f32_16x16x32_bf16 v[16:19], v[156:159], v[168:171], v[16:19]
	v_mfma_f32_16x16x32_bf16 v[12:15], v[156:159], v[172:175], v[12:15]
	v_mfma_f32_16x16x32_bf16 v[8:11], v[156:159], v[176:179], v[8:11]
	v_mfma_f32_16x16x32_bf16 v[4:7], v[160:163], v[164:167], v[4:7]
	v_mfma_f32_16x16x32_bf16 v[0:3], v[160:163], v[168:171], v[0:3]
	v_mfma_f32_16x16x32_bf16 v[92:95], v[160:163], v[172:175], v[92:95]
	v_mfma_f32_16x16x32_bf16 v[84:87], v[160:163], v[176:179], v[84:87]
	v_add3_u32 v132, v141, v146, s28
	ds_read_b128 v[128:131], v132 offset:14336
	ds_read_b128 v[134:137], v132 offset:12288
	ds_read_b128 v[148:151], v132 offset:10240
	ds_read_b128 v[152:155], v132 offset:8192
	ds_read_b128 v[156:159], v132 offset:6144
	ds_read_b128 v[160:163], v132 offset:4096
	ds_read_b128 v[164:167], v132 offset:2048
	ds_read_b128 v[168:171], v132
	v_add3_u32 v132, v143, v146, s27
	ds_read_b128 v[144:147], v132 offset:6144
	ds_read_b128 v[172:175], v132 offset:4096
	ds_read_b128 v[176:179], v132 offset:2048
	ds_read_b128 v[180:183], v132
	s_waitcnt lgkmcnt(0)
	v_mfma_f32_16x16x32_bf16 v[124:127], v[168:171], v[180:183], v[124:127]
	v_mfma_f32_16x16x32_bf16 v[120:123], v[168:171], v[176:179], v[120:123]
	v_mfma_f32_16x16x32_bf16 v[116:119], v[168:171], v[172:175], v[116:119]
	v_mfma_f32_16x16x32_bf16 v[112:115], v[168:171], v[144:147], v[112:115]
	v_mfma_f32_16x16x32_bf16 v[108:111], v[164:167], v[180:183], v[108:111]
	v_mfma_f32_16x16x32_bf16 v[104:107], v[164:167], v[176:179], v[104:107]
	v_mfma_f32_16x16x32_bf16 v[100:103], v[164:167], v[172:175], v[100:103]
	v_mfma_f32_16x16x32_bf16 v[96:99], v[164:167], v[144:147], v[96:99]
	v_mfma_f32_16x16x32_bf16 v[88:91], v[160:163], v[180:183], v[88:91]
	v_mfma_f32_16x16x32_bf16 v[80:83], v[160:163], v[176:179], v[80:83]
	v_mfma_f32_16x16x32_bf16 v[76:79], v[160:163], v[172:175], v[76:79]
	v_mfma_f32_16x16x32_bf16 v[72:75], v[160:163], v[144:147], v[72:75]
	v_mfma_f32_16x16x32_bf16 v[68:71], v[156:159], v[180:183], v[68:71]
	v_mfma_f32_16x16x32_bf16 v[64:67], v[156:159], v[176:179], v[64:67]
	v_mfma_f32_16x16x32_bf16 v[56:59], v[156:159], v[144:147], v[56:59]
	v_mfma_f32_16x16x32_bf16 v[160:163], v[156:159], v[172:175], v[60:63]
	s_nop 2
	v_add3_u32 v60, v143, v142, s27
	ds_read_b128 v[156:159], v60
	ds_read_b128 v[164:167], v60 offset:2048
	ds_read_b128 v[168:171], v60 offset:4096
	ds_read_b128 v[186:189], v60 offset:6144
	v_add3_u32 v60, v141, v142, s28
	ds_read_b128 v[138:141], v60
	ds_read_b128 v[190:193], v60 offset:2048
	ds_read_b128 v[194:197], v60 offset:4096
	ds_read_b128 v[198:201], v60 offset:6144
	v_mfma_f32_16x16x32_bf16 v[44:47], v[152:155], v[172:175], v[44:47]
	v_mfma_f32_16x16x32_bf16 v[32:35], v[148:151], v[176:179], v[32:35]
	v_mfma_f32_16x16x32_bf16 v[28:31], v[148:151], v[172:175], v[28:31]
	v_mfma_f32_16x16x32_bf16 v[16:19], v[134:137], v[176:179], v[16:19]
	v_mfma_f32_16x16x32_bf16 v[202:205], v[152:155], v[180:183], v[52:55]
	v_mfma_f32_16x16x32_bf16 v[206:209], v[152:155], v[176:179], v[48:51]
	v_mfma_f32_16x16x32_bf16 v[152:155], v[152:155], v[144:147], v[40:43]
	v_mfma_f32_16x16x32_bf16 v[210:213], v[148:151], v[180:183], v[36:39]
	v_mfma_f32_16x16x32_bf16 v[148:151], v[148:151], v[144:147], v[24:27]
	v_mfma_f32_16x16x32_bf16 v[214:217], v[134:137], v[180:183], v[20:23]
	v_mfma_f32_16x16x32_bf16 v[218:221], v[134:137], v[172:175], v[12:15]
	v_mfma_f32_16x16x32_bf16 v[222:225], v[134:137], v[144:147], v[8:11]
	v_mfma_f32_16x16x32_bf16 v[180:183], v[128:131], v[180:183], v[4:7]
	v_mfma_f32_16x16x32_bf16 v[176:179], v[128:131], v[176:179], v[0:3]
	v_mfma_f32_16x16x32_bf16 v[172:175], v[128:131], v[172:175], v[92:95]
	v_mfma_f32_16x16x32_bf16 v[142:145], v[128:131], v[144:147], v[84:87]
	s_nop 0
	ds_read_b128 v[0:3], v60 offset:8192
	ds_read_b128 v[128:131], v60 offset:10240
	ds_read_b128 v[226:229], v60 offset:12288
	ds_read_b128 v[230:233], v60 offset:14336
	s_waitcnt lgkmcnt(0)
	v_mfma_f32_16x16x32_bf16 v[124:127], v[138:141], v[156:159], v[124:127]
	v_mfma_f32_16x16x32_bf16 v[92:95], v[138:141], v[164:167], v[120:123]
	v_mfma_f32_16x16x32_bf16 v[60:63], v[138:141], v[168:171], v[116:119]
	v_mfma_f32_16x16x32_bf16 v[24:27], v[138:141], v[186:189], v[112:115]
	v_mfma_f32_16x16x32_bf16 v[120:123], v[190:193], v[156:159], v[108:111]
	v_mfma_f32_16x16x32_bf16 v[84:87], v[190:193], v[164:167], v[104:107]
	v_mfma_f32_16x16x32_bf16 v[52:55], v[190:193], v[168:171], v[100:103]
	v_mfma_f32_16x16x32_bf16 v[20:23], v[190:193], v[186:189], v[96:99]
	v_mfma_f32_16x16x32_bf16 v[112:115], v[194:197], v[156:159], v[88:91]
	v_mfma_f32_16x16x32_bf16 v[80:83], v[194:197], v[164:167], v[80:83]
	v_mfma_f32_16x16x32_bf16 v[48:51], v[194:197], v[168:171], v[76:79]
	v_mfma_f32_16x16x32_bf16 v[12:15], v[194:197], v[186:189], v[72:75]
	v_mfma_f32_16x16x32_bf16 v[108:111], v[198:201], v[156:159], v[68:71]
	v_mfma_f32_16x16x32_bf16 v[76:79], v[198:201], v[164:167], v[64:67]
	v_mfma_f32_16x16x32_bf16 v[40:43], v[198:201], v[168:171], v[160:163]
	v_mfma_f32_16x16x32_bf16 v[8:11], v[198:201], v[186:189], v[56:59]
	s_waitcnt vmcnt(0)
	v_mov_b32_e32 v135, v184
	v_mfma_f32_16x16x32_bf16 v[64:67], v[128:131], v[164:167], v[32:35]
	s_waitcnt lgkmcnt(0)
	s_barrier
	v_mfma_f32_16x16x32_bf16 v[32:35], v[128:131], v[168:171], v[28:31]
	v_cvt_pk_bf16_f32 v132, v124, v125
	v_cvt_pk_bf16_f32 v134, v126, v127
	v_mfma_f32_16x16x32_bf16 v[104:107], v[0:3], v[156:159], v[202:205]
	v_and_b32_e32 v28, 16, v135
	v_cmp_eq_u32_e64 s[2:3], 0, v28
	v_cmp_ne_u32_e32 vcc, 0, v28
	v_mfma_f32_16x16x32_bf16 v[68:71], v[0:3], v[164:167], v[206:209]
	v_cvt_pk_bf16_f32 v136, v120, v121
	v_cvt_pk_bf16_f32 v137, v122, v123
	v_mfma_f32_16x16x32_bf16 v[36:39], v[0:3], v[168:171], v[44:47]
	v_mfma_f32_16x16x32_bf16 v[4:7], v[0:3], v[186:189], v[152:155]
	v_mfma_f32_16x16x32_bf16 v[100:103], v[128:131], v[156:159], v[210:213]
	v_mfma_f32_16x16x32_bf16 v[0:3], v[128:131], v[186:189], v[148:151]
	v_mov_b32_e32 v128, v132
	v_mov_b32_e32 v130, v136
	v_mov_b32_e32 v129, v134
	v_mfma_f32_16x16x32_bf16 v[96:99], v[226:229], v[156:159], v[214:217]
	v_mov_b32_e32 v131, v137
	v_permlane16_swap_b32_e32 v128, v130
	v_mfma_f32_16x16x32_bf16 v[72:75], v[226:229], v[164:167], v[16:19]
	v_permlane16_swap_b32_e32 v129, v131
	v_mfma_f32_16x16x32_bf16 v[44:47], v[226:229], v[168:171], v[218:221]
	v_mfma_f32_16x16x32_bf16 v[16:19], v[226:229], v[186:189], v[222:225]
	v_mfma_f32_16x16x32_bf16 v[116:119], v[230:233], v[156:159], v[180:183]
	v_mfma_f32_16x16x32_bf16 v[88:91], v[230:233], v[164:167], v[176:179]
	v_mfma_f32_16x16x32_bf16 v[56:59], v[230:233], v[168:171], v[172:175]
	v_mfma_f32_16x16x32_bf16 v[28:31], v[230:233], v[186:189], v[142:145]
	s_and_saveexec_b64 s[12:13], vcc
	s_xor_b64 s[12:13], exec, s[12:13]
	v_mov_b32_e32 v131, v137
	v_mov_b32_e32 v130, v136
	s_andn2_saveexec_b64 s[12:13], s[12:13]
	v_mov_b32_e32 v128, v132
	v_mov_b32_e32 v129, v134
	s_or_b64 exec, exec, s[12:13]
	v_ashrrev_i32_e32 v134, 8, v135
	v_bfe_u32 v132, v135, 4, 2
	v_and_b32_e32 v135, 0xcf, v135
	v_lshlrev_b32_e32 v136, 2, v132
	v_lshl_or_b32 v138, s10, 8, v135
	v_add_u32_e32 v137, 12, v136
	v_ashrrev_i32_e32 v139, 31, v138
	v_cndmask_b32_e64 v136, v137, v136, s[2:3]
	v_lshlrev_b64 v[140:141], 11, v[138:139]
	s_lshl_b32 s8, s30, 8
	v_lshl_or_b32 v136, v134, 7, v136
	v_lshl_add_u64 v[140:141], s[4:5], 0, v[140:141]
	v_lshl_add_u64 v[140:141], s[8:9], 1, v[140:141]
	v_ashrrev_i32_e32 v137, 31, v136
	v_lshl_add_u64 v[140:141], v[136:137], 1, v[140:141]
	v_cvt_pk_bf16_f32 v135, v112, v113
	v_cvt_pk_bf16_f32 v142, v114, v115
	v_cvt_pk_bf16_f32 v143, v108, v109
	v_cvt_pk_bf16_f32 v144, v110, v111
	global_store_dwordx4 v[140:141], v[128:131], off
	s_nop 1
	v_mov_b32_e32 v130, v143
	v_mov_b32_e32 v128, v135
	v_mov_b32_e32 v131, v144
	v_mov_b32_e32 v129, v142
	v_permlane16_swap_b32_e32 v128, v130
	s_nop 0
	v_permlane16_swap_b32_e32 v129, v131
	s_and_saveexec_b64 s[2:3], vcc
	s_xor_b64 s[2:3], exec, s[2:3]
	v_mov_b32_e32 v131, v144
	v_mov_b32_e32 v130, v143
	s_andn2_saveexec_b64 s[2:3], s[2:3]
	v_mov_b32_e32 v128, v135
	v_mov_b32_e32 v129, v142
	s_or_b64 exec, exec, s[2:3]
	v_cvt_pk_bf16_f32 v135, v104, v105
	v_cvt_pk_bf16_f32 v142, v106, v107
	v_cvt_pk_bf16_f32 v143, v100, v101
	v_cvt_pk_bf16_f32 v144, v102, v103
	global_store_dwordx4 v[140:141], v[128:131], off offset:64
	s_nop 1
	v_mov_b32_e32 v130, v143
	v_mov_b32_e32 v128, v135
	v_mov_b32_e32 v131, v144
	v_mov_b32_e32 v129, v142
	v_permlane16_swap_b32_e32 v128, v130
	s_nop 0
	v_permlane16_swap_b32_e32 v129, v131
	s_and_saveexec_b64 s[2:3], vcc
	s_xor_b64 s[2:3], exec, s[2:3]
	v_mov_b32_e32 v131, v144
	v_mov_b32_e32 v130, v143
	s_andn2_saveexec_b64 s[2:3], s[2:3]
	v_mov_b32_e32 v128, v135
	v_mov_b32_e32 v129, v142
	s_or_b64 exec, exec, s[2:3]
	v_cvt_pk_bf16_f32 v135, v96, v97
	v_cvt_pk_bf16_f32 v142, v98, v99
	v_cvt_pk_bf16_f32 v143, v116, v117
	v_cvt_pk_bf16_f32 v144, v118, v119
	global_store_dwordx4 v[140:141], v[128:131], off offset:128
	s_nop 1
	v_mov_b32_e32 v130, v143
	v_mov_b32_e32 v128, v135
	v_mov_b32_e32 v131, v144
	v_mov_b32_e32 v129, v142
	v_permlane16_swap_b32_e32 v128, v130
	s_nop 0
	v_permlane16_swap_b32_e32 v129, v131
	s_and_saveexec_b64 s[2:3], vcc
	s_xor_b64 s[2:3], exec, s[2:3]
	v_mov_b32_e32 v131, v144
	v_mov_b32_e32 v130, v143
	s_andn2_saveexec_b64 s[2:3], s[2:3]
	v_mov_b32_e32 v128, v135
	v_mov_b32_e32 v129, v142
	s_or_b64 exec, exec, s[2:3]
	v_mul_f32_e32 v125, v125, v125
	v_mul_f32_e32 v113, v113, v113
	v_fmac_f32_e32 v125, v124, v124
	v_fmac_f32_e32 v113, v112, v112
	v_mul_f32_e32 v105, v105, v105
	v_fmac_f32_e32 v125, v126, v126
	v_fmac_f32_e32 v113, v114, v114
	v_fmac_f32_e32 v105, v104, v104
	v_mul_f32_e32 v97, v97, v97
	v_fmac_f32_e32 v125, v127, v127
	v_fmac_f32_e32 v113, v115, v115
	v_fmac_f32_e32 v105, v106, v106
	v_fmac_f32_e32 v97, v96, v96
	v_fmac_f32_e32 v125, v120, v120
	v_fmac_f32_e32 v113, v108, v108
	v_fmac_f32_e32 v105, v107, v107
	v_fmac_f32_e32 v97, v98, v98
	v_fmac_f32_e32 v125, v121, v121
	v_fmac_f32_e32 v113, v109, v109
	v_fmac_f32_e32 v105, v100, v100
	v_fmac_f32_e32 v97, v99, v99
	v_fmac_f32_e32 v125, v122, v122
	v_fmac_f32_e32 v113, v110, v110
	v_fmac_f32_e32 v105, v101, v101
	v_fmac_f32_e32 v97, v116, v116
	v_fmac_f32_e32 v125, v123, v123
	v_fmac_f32_e32 v113, v111, v111
	v_fmac_f32_e32 v105, v102, v102
	v_fmac_f32_e32 v97, v117, v117
	v_add_f32_e32 v108, v125, v113
	v_fmac_f32_e32 v105, v103, v103
	v_fmac_f32_e32 v97, v118, v118
	v_add_f32_e32 v100, v108, v105
	v_fmac_f32_e32 v97, v119, v119
	v_add_f32_e32 v96, v100, v97
	v_mov_b32_e32 v97, v96
	s_nop 1
	v_permlane16_swap_b32_e32 v96, v97
	v_add_f32_e32 v96, v96, v97
	v_mov_b32_e32 v97, v96
	v_cmp_eq_u32_e64 s[2:3], 0, v132
	v_ashrrev_i32_e32 v135, 31, v134
	v_permlane32_swap_b32_e32 v96, v97
	global_store_dwordx4 v[140:141], v[128:131], off offset:192
	s_and_saveexec_b64 s[12:13], s[2:3]
	s_cbranch_execz .LBB0_2021
	v_add_f32_e32 v98, v96, v97
	v_lshlrev_b64 v[96:97], 5, v[138:139]
	s_lshl_b32 s34, s30, 1
	s_mov_b32 s35, s9
	v_lshl_add_u64 v[96:97], s[6:7], 0, v[96:97]
	v_lshl_add_u64 v[96:97], s[34:35], 2, v[96:97]
	v_lshl_add_u64 v[96:97], v[134:135], 2, v[96:97]
	global_store_dword v[96:97], v98, off
